# m1h
# speedup vs baseline: 1.0242x; 1.0127x over previous
; __global__ void __launch_bounds__(512, 2) fwd_megakernel(Params kp_) {
;     ...
;                                     float r[16];
; #pragma unroll
;                                     for (int i = 0; i < 16; ++i) { const int row = ib * 16 + i; float v0 = X[row * 128] * bet[row]; if (!isu) v0 *= __expf(gc[row]); r[i] = v0; }
.LBB0_755:
	s_lshl_b32 s27, s21, 4
	v_lshl_add_u32 v67, s21, 13, v104
	ds_read2st64_b32 v[34:35], v67 offset1:2
	ds_read2st64_b32 v[36:37], v67 offset0:4 offset1:6
	ds_read2st64_b32 v[38:39], v67 offset0:8 offset1:10
	ds_read2st64_b32 v[40:41], v67 offset0:12 offset1:14
	ds_read2st64_b32 v[42:43], v67 offset0:16 offset1:18
	ds_read2st64_b32 v[44:45], v67 offset0:20 offset1:22
	ds_read2st64_b32 v[46:47], v67 offset0:24 offset1:26
	ds_read2st64_b32 v[48:49], v67 offset0:28 offset1:30
	s_lshl_b32 s18, s21, 6
	s_add_i32 s19, s18, 0x20900
	v_mov_b32_e32 v50, s19
	ds_read_b128 v[16:19], v50
	ds_read_b128 v[20:23], v50 offset:16
	ds_read_b128 v[24:27], v50 offset:32
	ds_read_b128 v[28:31], v50 offset:48
	s_add_i32 s19, s18, 0x20800
	v_mov_b32_e32 v51, s19
	ds_read_b128 v[0:3], v51
	ds_read_b128 v[4:7], v51 offset:16
	ds_read_b128 v[8:11], v51 offset:32
	ds_read_b128 v[12:15], v51 offset:48
	s_or_b32 s94, s27, 1
	s_or_b32 s6, s27, 2
	s_or_b32 s8, s27, 3
	s_or_b32 s9, s27, 4
	s_or_b32 s25, s27, 5
	s_or_b32 s22, s27, 6
	s_or_b32 s23, s27, 7
	s_or_b32 s26, s27, 8
	s_or_b32 vcc_lo, s27, 9
	s_or_b32 vcc_hi, s27, 10
	s_or_b32 s7, s27, 11
	s_or_b32 s33, s27, 12
	s_or_b32 s24, s27, 13
	s_or_b32 s4, s27, 14
	s_or_b32 s5, s27, 15
	s_waitcnt lgkmcnt(0)
	v_mul_f32_e32 v34, v34, v16
	v_mul_f32_e32 v35, v35, v17
	v_mul_f32_e32 v36, v36, v18
	v_mul_f32_e32 v37, v37, v19
	v_mul_f32_e32 v38, v38, v20
	v_mul_f32_e32 v39, v39, v21
	v_mul_f32_e32 v40, v40, v22
	v_mul_f32_e32 v41, v41, v23
	v_mul_f32_e32 v42, v42, v24
	v_mul_f32_e32 v43, v43, v25
	v_mul_f32_e32 v44, v44, v26
	v_mul_f32_e32 v45, v45, v27
	v_mul_f32_e32 v46, v46, v28
	v_mul_f32_e32 v47, v47, v29
	v_mul_f32_e32 v48, v48, v30
	v_mul_f32_e32 v49, v49, v31
	s_and_saveexec_b64 s[18:19], s[10:11]
	s_cbranch_execz .Lm1h_skip
	v_mul_f32_e32 v0, 0x3fb8aa3b, v0
	v_mul_f32_e32 v1, 0x3fb8aa3b, v1
	v_mul_f32_e32 v2, 0x3fb8aa3b, v2
	v_mul_f32_e32 v3, 0x3fb8aa3b, v3
	v_mul_f32_e32 v4, 0x3fb8aa3b, v4
	v_mul_f32_e32 v5, 0x3fb8aa3b, v5
	v_mul_f32_e32 v6, 0x3fb8aa3b, v6
	v_mul_f32_e32 v7, 0x3fb8aa3b, v7
	v_mul_f32_e32 v8, 0x3fb8aa3b, v8
	v_mul_f32_e32 v9, 0x3fb8aa3b, v9
	v_mul_f32_e32 v10, 0x3fb8aa3b, v10
	v_mul_f32_e32 v11, 0x3fb8aa3b, v11
	v_mul_f32_e32 v12, 0x3fb8aa3b, v12
	v_mul_f32_e32 v13, 0x3fb8aa3b, v13
	v_mul_f32_e32 v14, 0x3fb8aa3b, v14
	v_mul_f32_e32 v15, 0x3fb8aa3b, v15
	v_exp_f32_e32 v0, v0
	v_exp_f32_e32 v1, v1
	v_exp_f32_e32 v2, v2
	v_exp_f32_e32 v3, v3
	v_exp_f32_e32 v4, v4
	v_exp_f32_e32 v5, v5
	v_exp_f32_e32 v6, v6
	v_exp_f32_e32 v7, v7
	v_exp_f32_e32 v8, v8
	v_exp_f32_e32 v9, v9
	v_exp_f32_e32 v10, v10
	v_exp_f32_e32 v11, v11
	v_exp_f32_e32 v12, v12
	v_exp_f32_e32 v13, v13
	v_exp_f32_e32 v14, v14
	v_exp_f32_e32 v15, v15
	v_mul_f32_e32 v34, v34, v0
	v_mul_f32_e32 v35, v35, v1
	v_mul_f32_e32 v36, v36, v2
	v_mul_f32_e32 v37, v37, v3
	v_mul_f32_e32 v38, v38, v4
	v_mul_f32_e32 v39, v39, v5
	v_mul_f32_e32 v40, v40, v6
	v_mul_f32_e32 v41, v41, v7
	v_mul_f32_e32 v42, v42, v8
	v_mul_f32_e32 v43, v43, v9
	v_mul_f32_e32 v44, v44, v10
	v_mul_f32_e32 v45, v45, v11
	v_mul_f32_e32 v46, v46, v12
	v_mul_f32_e32 v47, v47, v13
	v_mul_f32_e32 v48, v48, v14
	v_mul_f32_e32 v49, v49, v15
